# activation seam fix-up loop: both load batches issued together (three destinations renamed), on top of the combined version
# baseline (speedup 1.0000x reference)
; DEV float gelu_t(float x) { const float u = x * (0.7978845608f + 0.0356774081f * x * x); return x * __builtin_amdgcn_rcpf(1.f + __builtin_amdgcn_exp2f(-2.885390082f * u)); }
; DEV u32x4 pack8(const float (&f)[8]) { u32x4 w; w.x = cvt_pk_bf16(f[0], f[1]); w.y = cvt_pk_bf16(f[2], f[3]); w.z = cvt_pk_bf16(f[4], f[5]); w.w = cvt_pk_bf16(f[6], f[7]); return w; }
; DEV void phase_actfix(const float* GL, const float* GF, const float* cw, bf16_t* ACT, int pm0, int npm) {
;     ...
;     for (int idx = tid; idx < npm * 768; idx += 512) {
;         const int pm = pm0 + idx / 768, r = idx % 768, t = r / 384, c = (r - t * 384) * 8;
;         const bool first = (pm & 7) == 0;
;         const float* gf = GF + ((size_t)(pm * 2 + t) * 2) * DFF + c;
;         const float* gl = GL + (size_t)(first ? 0 : pm - 1) * 2 * DFF + c;
;         const float* gm1p = t == 0 ? gl + DFF : GF + ((size_t)(pm * 2) * 2) * DFF + c;
;         const float* gm2p = t == 0 ? gl : gl + DFF;
;         float y[8];
; #pragma unroll
;         for (int hf = 0; hf < 2; ++hf) { const f32x4 g0 = *(const f32x4*)(gf + hf * 4), vv = *(const f32x4*)(gf + DFF + hf * 4);
;             f32x4 gm1 = *(const f32x4*)(gm1p + hf * 4), gm2 = *(const f32x4*)(gm2p + hf * 4);
;             if (first) { gm2 = (f32x4){0.f, 0.f, 0.f, 0.f}; if (t == 0) gm1 = gm2; }
;             const f32x4 w0 = *(const f32x4*)(cw + c + hf * 4), w1 = *(const f32x4*)(cw + DFF + c + hf * 4), w2 = *(const f32x4*)(cw + 2 * DFF + c + hf * 4);
; #pragma unroll
;             for (int j = 0; j < 4; ++j) y[hf * 4 + j] = gelu_t(w0[j] * gm2[j] + w1[j] * gm1[j] + w2[j] * g0[j]) * vv[j]; }
;         *(u32x4*)(ACT + ((size_t)pm * 256 + t) * DFF + c) = pack8(y);
;     }
.LBB0_466:
	s_or_b64 exec, exec, s[6:7]
	v_add_u32_sdwa v8, v7, sext(v6) dst_sel:DWORD dst_unused:UNUSED_PAD src0_sel:DWORD src1_sel:WORD_0
	v_mov_b64_e32 v[6:7], s[46:47]
	v_mad_i64_i32 v[6:7], s[6:7], v8, s10, v[6:7]
	v_lshlrev_b64 v[8:9], 2, v[26:27]
	v_lshl_add_u64 v[12:13], v[6:7], 0, v[8:9]
	v_lshl_add_u64 v[14:15], v[2:3], 0, v[4:5]
	s_or_b64 s[40:41], vcc, s[42:43]
	v_add_co_u32_e32 v4, vcc, s11, v12
	v_lshl_add_u64 v[2:3], v[12:13], 0, s[28:29]
	s_nop 0
	v_addc_co_u32_e32 v5, vcc, 0, v13, vcc
	v_lshl_add_u64 v[18:19], s[4:5], 0, v[8:9]
	v_lshl_add_u64 v[20:21], s[50:51], 0, v[8:9]
	v_lshl_add_u64 v[40:41], s[52:53], 0, v[8:9]
	global_load_dwordx4 v[6:9], v[12:13], off offset:16
	global_load_dwordx4 v[32:35], v[12:13], off
	global_load_dwordx4 v[36:39], v[4:5], off
	s_nop 0
	global_load_dwordx4 v[2:5], v[2:3], off offset:16
	s_nop 0
	global_load_dwordx4 v[22:25], v[10:11], off offset:16
	s_nop 0
	global_load_dwordx4 v[10:13], v[10:11], off
	s_nop 0
	global_load_dwordx4 v[42:45], v[14:15], off offset:16
	s_nop 0
	global_load_dwordx4 v[14:17], v[14:15], off
	global_load_dwordx4 v[68:71], v[18:19], off offset:16
	global_load_dwordx4 v[46:49], v[18:19], off
	global_load_dwordx4 v[72:75], v[20:21], off offset:16
	global_load_dwordx4 v[50:53], v[20:21], off
	global_load_dwordx4 v[76:79], v[40:41], off offset:16
	global_load_dwordx4 v[54:57], v[40:41], off
	s_waitcnt vmcnt(9)
	v_cndmask_b32_e64 v22, 0, v22, s[40:41]
	s_waitcnt vmcnt(8)
	v_cndmask_b32_e64 v66, 0, v13, s[40:41]
	v_cndmask_b32_e64 v58, 0, v12, s[40:41]
	s_waitcnt vmcnt(6)
	v_cndmask_b32_e64 v59, 0, v17, s[42:43]
	v_cndmask_b32_e64 v61, 0, v16, s[42:43]
	v_cndmask_b32_e64 v63, 0, v15, s[42:43]
	v_cndmask_b32_e64 v65, 0, v14, s[42:43]
	v_cndmask_b32_e64 v31, 0, v11, s[40:41]
	v_cndmask_b32_e64 v29, 0, v10, s[40:41]
	s_nop 0
	v_mov_b32_e32 v40, v32
	v_cndmask_b32_e64 v23, 0, v23, s[40:41]
	v_cndmask_b32_e64 v24, 0, v24, s[40:41]
	v_cndmask_b32_e64 v25, 0, v25, s[40:41]
	s_waitcnt vmcnt(4)
	v_mov_b32_e32 v41, v46
	v_mov_b32_e32 v46, v33
	s_waitcnt vmcnt(0)
	v_mov_b32_e32 v64, v54
	v_pk_mul_f32 v[40:41], v[40:41], v[64:65]
	v_mov_b32_e32 v62, v55
	v_fma_f32 v29, v29, v50, v41
	v_add_f32_e32 v29, v40, v29
	v_mul_f32_e32 v32, 0x3d122279, v29
	v_fmaak_f32 v32, v29, v32, 0x3f4c422a
	v_mul_f32_e32 v32, v29, v32
	v_mul_f32_e32 v32, 0xc038aa3b, v32
	v_exp_f32_e32 v32, v32
	v_mov_b32_e32 v60, v56
	v_add_f32_e32 v32, 1.0, v32
	v_rcp_f32_e32 v32, v32
	s_nop 0
	v_mul_f32_e32 v29, v29, v32
	v_pk_mul_f32 v[32:33], v[46:47], v[62:63]
	v_mul_f32_e32 v29, v36, v29
	v_fma_f32 v31, v31, v51, v33
	v_add_f32_e32 v31, v32, v31
	v_mul_f32_e32 v32, 0x3d122279, v31
	v_fmaak_f32 v32, v31, v32, 0x3f4c422a
	v_mul_f32_e32 v32, v31, v32
	v_mul_f32_e32 v32, 0xc038aa3b, v32
	v_exp_f32_e32 v32, v32
	v_mov_b32_e32 v33, v48
	v_mov_b32_e32 v48, v35
	v_mov_b32_e32 v36, v77
	v_add_f32_e32 v32, 1.0, v32
	v_rcp_f32_e32 v32, v32
	v_cndmask_b32_e64 v35, 0, v44, s[42:43]
	v_mul_f32_e32 v31, v31, v32
	v_mov_b32_e32 v32, v34
	v_pk_mul_f32 v[32:33], v[32:33], v[60:61]
	v_mul_f32_e32 v31, v37, v31
	v_fma_f32 v33, v58, v52, v33
	v_add_f32_e32 v32, v32, v33
	v_mul_f32_e32 v33, 0x3d122279, v32
	v_fmaak_f32 v33, v32, v33, 0x3f4c422a
	v_mul_f32_e32 v33, v32, v33
	v_mul_f32_e32 v33, 0xc038aa3b, v33
	v_exp_f32_e32 v33, v33
	v_mov_b32_e32 v58, v57
	v_cndmask_b32_e64 v37, 0, v43, s[42:43]
	v_mov_b32_e32 v43, v68
	v_add_f32_e32 v33, 1.0, v33
	v_rcp_f32_e32 v33, v33
	v_mov_b32_e32 v34, v78
	v_mul_f32_e32 v32, v32, v33
	v_mul_f32_e32 v40, v38, v32
	v_pk_mul_f32 v[32:33], v[48:49], v[58:59]
	v_mov_b32_e32 v38, v76
	v_fma_f32 v33, v66, v53, v33
	v_add_f32_e32 v32, v32, v33
	v_mul_f32_e32 v33, 0x3d122279, v32
	v_fmaak_f32 v33, v32, v33, 0x3f4c422a
	v_mul_f32_e32 v33, v32, v33
	v_mul_f32_e32 v33, 0xc038aa3b, v33
	v_exp_f32_e32 v33, v33
	s_nop 0
	v_add_f32_e32 v33, 1.0, v33
	v_rcp_f32_e32 v33, v33
	s_nop 0
	v_mul_f32_e32 v32, v32, v33
	v_mul_f32_e32 v41, v39, v32
	v_cndmask_b32_e64 v39, 0, v42, s[42:43]
	v_mov_b32_e32 v42, v6
	v_pk_mul_f32 v[38:39], v[42:43], v[38:39]
	v_cndmask_b32_e64 v33, 0, v45, s[42:43]
	v_fma_f32 v6, v22, v72, v39
	v_add_f32_e32 v6, v38, v6
	v_mul_f32_e32 v68, 0x3d122279, v6
	v_fmaak_f32 v68, v6, v68, 0x3f4c422a
	v_mul_f32_e32 v68, v6, v68
	v_mul_f32_e32 v68, 0xc038aa3b, v68
	v_exp_f32_e32 v68, v68
	v_mov_b32_e32 v32, v79
	v_add_f32_e32 v68, 1.0, v68
	v_rcp_f32_e32 v68, v68
	s_nop 0
	v_mul_f32_e32 v6, v6, v68
	v_mov_b32_e32 v68, v7
	v_mul_f32_e32 v72, v2, v6
	v_pk_mul_f32 v[6:7], v[68:69], v[36:37]
	s_nop 0
	v_fma_f32 v2, v23, v73, v7
	v_add_f32_e32 v2, v6, v2
	v_mul_f32_e32 v6, 0x3d122279, v2
	v_fmaak_f32 v6, v2, v6, 0x3f4c422a
	v_mul_f32_e32 v6, v2, v6
	v_mul_f32_e32 v6, 0xc038aa3b, v6
	v_exp_f32_e32 v6, v6
	s_nop 0
	v_add_f32_e32 v6, 1.0, v6
	v_rcp_f32_e32 v6, v6
	s_nop 0
	v_mul_f32_e32 v2, v2, v6
	v_mul_f32_e32 v6, v3, v2
	v_mov_b32_e32 v2, v8
	v_mov_b32_e32 v3, v70
	v_pk_mul_f32 v[2:3], v[2:3], v[34:35]
	v_mov_b32_e32 v70, v9
	v_fma_f32 v3, v24, v74, v3
	v_add_f32_e32 v2, v2, v3
	v_mul_f32_e32 v3, 0x3d122279, v2
	v_fmaak_f32 v3, v2, v3, 0x3f4c422a
	v_mul_f32_e32 v3, v2, v3
	v_mul_f32_e32 v3, 0xc038aa3b, v3
	v_exp_f32_e32 v3, v3
	v_mov_b64_e32 v[8:9], s[22:23]
	v_add_f32_e32 v3, 1.0, v3
	v_rcp_f32_e32 v3, v3
	s_nop 0
	v_mul_f32_e32 v2, v2, v3
	v_mul_f32_e32 v7, v4, v2
	v_pk_mul_f32 v[2:3], v[70:71], v[32:33]
	s_nop 0
	v_fma_f32 v3, v25, v75, v3
	v_add_f32_e32 v2, v2, v3
	v_mul_f32_e32 v3, 0x3d122279, v2
	v_fmaak_f32 v3, v2, v3, 0x3f4c422a
	v_mul_f32_e32 v3, v2, v3
	v_mul_f32_e32 v3, 0xc038aa3b, v3
	v_exp_f32_e32 v3, v3
	s_nop 0
	v_add_f32_e32 v3, 1.0, v3
	v_rcp_f32_e32 v3, v3
	s_nop 0
	v_mul_f32_e32 v2, v2, v3
	v_mul_f32_e32 v5, v5, v2
	v_cvt_pk_bf16_f32 v2, v29, v31
	v_ashrrev_i32_e32 v29, 31, v28
	v_cvt_pk_bf16_f32 v3, v40, v41
	v_cvt_pk_bf16_f32 v4, v72, v6
	v_cvt_pk_bf16_f32 v5, v7, v5
	v_lshlrev_b64 v[6:7], 8, v[28:29]
	v_ashrrev_i32_e32 v31, 31, v30
	v_lshl_add_u64 v[6:7], v[6:7], 0, v[30:31]
	v_mad_u64_u32 v[8:9], s[6:7], v6, s74, v[8:9]
	v_mad_i32_i24 v9, v7, s74, v9
	v_lshl_add_u64 v[6:7], v[26:27], 1, v[8:9]
	s_movk_i32 s6, 0xff
	global_store_dwordx4 v[6:7], v[2:5], off
	v_cmp_lt_i32_e32 vcc, s6, v0
	s_or_b64 s[54:55], vcc, s[54:55]
	v_add_u32_e32 v2, 0x200, v0
	v_mov_b32_e32 v0, v2
	s_andn2_b64 exec, exec, s[54:55]
	s_cbranch_execz .LBB0_455
